# grid barrier: last XCD leader no longer waits for unused TOPGEN ack; unused XGEN add removed
# baseline (speedup 1.0000x reference)
; __device__ __forceinline__ unsigned xb_ld(unsigned* p)              { return __hip_atomic_load(p, __ATOMIC_RELAXED, __HIP_MEMORY_SCOPE_AGENT); }
; __device__ __forceinline__ unsigned xb_add(unsigned* p, unsigned v) { return __hip_atomic_fetch_add(p, v, __ATOMIC_RELAXED, __HIP_MEMORY_SCOPE_AGENT); }
; #define XB_SPIN(cond, bar) do { unsigned _sp = 0; while (cond) { __builtin_amdgcn_s_sleep(1); \
;     if ((++_sp & 255u) == 0u) { if (xb_ld(&(bar)[XB_TMO])) break; if (_sp > XB_SPIN_CAP) { atomicAdd(&(bar)[XB_TMO], 1u); break; } } } } while (0)
; __device__ __forceinline__ void xcd_barrier(const XcdBarrier& b, bool leader_thread) {
;     ...
;             if (og + 1u == (tg + 1u) * nx) xb_add(&bar[XB_TOPGEN], 1u);
;             else XB_SPIN(xb_ld(&bar[XB_TOPGEN]) == tg, bar);
;             __builtin_amdgcn_fence(__ATOMIC_ACQUIRE, "agent");
;             xb_add(&bar[XB_XGEN(b.x)], 1u);
;             asm volatile("s_waitcnt vmcnt(0)" ::: "memory");
.LBB0_171:
	s_or_b64 exec, exec, s[4:5]
	s_mov_b64 s[4:5], exec
	v_mbcnt_lo_u32_b32 v0, s4, 0
	v_mbcnt_hi_u32_b32 v0, s5, v0
	v_cmp_eq_u32_e32 vcc, 0, v0
	s_and_saveexec_b64 s[6:7], vcc
	s_cbranch_execz .LBB0_173
	s_bcnt1_i32_b64 s2, s[4:5]
	v_mov_b32_e32 v0, s2
	v_readlane_b32 s2, v252, 55
	v_readlane_b32 s3, v252, 56
	s_nop 4

; __device__ __forceinline__ unsigned xb_ld(unsigned* p)              { return __hip_atomic_load(p, __ATOMIC_RELAXED, __HIP_MEMORY_SCOPE_AGENT); }
; __device__ __forceinline__ unsigned xb_add(unsigned* p, unsigned v) { return __hip_atomic_fetch_add(p, v, __ATOMIC_RELAXED, __HIP_MEMORY_SCOPE_AGENT); }
; #define XB_SPIN(cond, bar) do { unsigned _sp = 0; while (cond) { __builtin_amdgcn_s_sleep(1); \
;     if ((++_sp & 255u) == 0u) { if (xb_ld(&(bar)[XB_TMO])) break; if (_sp > XB_SPIN_CAP) { atomicAdd(&(bar)[XB_TMO], 1u); break; } } } } while (0)
; __device__ __forceinline__ void xcd_barrier(const XcdBarrier& b, bool leader_thread) {
;     ...
;             if (og + 1u == (tg + 1u) * nx) xb_add(&bar[XB_TOPGEN], 1u);
;             else XB_SPIN(xb_ld(&bar[XB_TOPGEN]) == tg, bar);
;             __builtin_amdgcn_fence(__ATOMIC_ACQUIRE, "agent");
;             xb_add(&bar[XB_XGEN(b.x)], 1u);
;             asm volatile("s_waitcnt vmcnt(0)" ::: "memory");
.LBB0_355:
	s_or_b64 exec, exec, s[8:9]
	s_mov_b64 s[8:9], exec
	v_mbcnt_lo_u32_b32 v0, s8, 0
	v_mbcnt_hi_u32_b32 v0, s9, v0
	v_cmp_eq_u32_e32 vcc, 0, v0
	s_and_saveexec_b64 s[10:11], vcc
	s_cbranch_execz .LBB0_357
	s_bcnt1_i32_b64 s3, s[8:9]
	v_readlane_b32 s6, v252, 55
	v_mov_b32_e32 v0, s3
	v_readlane_b32 s7, v252, 56
	s_nop 4

; __device__ __forceinline__ unsigned xb_ld(unsigned* p)              { return __hip_atomic_load(p, __ATOMIC_RELAXED, __HIP_MEMORY_SCOPE_AGENT); }
; __device__ __forceinline__ unsigned xb_add(unsigned* p, unsigned v) { return __hip_atomic_fetch_add(p, v, __ATOMIC_RELAXED, __HIP_MEMORY_SCOPE_AGENT); }
; #define XB_SPIN(cond, bar) do { unsigned _sp = 0; while (cond) { __builtin_amdgcn_s_sleep(1); \
;     if ((++_sp & 255u) == 0u) { if (xb_ld(&(bar)[XB_TMO])) break; if (_sp > XB_SPIN_CAP) { atomicAdd(&(bar)[XB_TMO], 1u); break; } } } } while (0)
; __device__ __forceinline__ void xcd_barrier(const XcdBarrier& b, bool leader_thread) {
;     ...
;             if (og + 1u == (tg + 1u) * nx) xb_add(&bar[XB_TOPGEN], 1u);
;             else XB_SPIN(xb_ld(&bar[XB_TOPGEN]) == tg, bar);
;             __builtin_amdgcn_fence(__ATOMIC_ACQUIRE, "agent");
;             xb_add(&bar[XB_XGEN(b.x)], 1u);
;             asm volatile("s_waitcnt vmcnt(0)" ::: "memory");
.LBB0_579:
	s_or_b64 exec, exec, s[6:7]
	s_mov_b64 s[6:7], exec
	v_mbcnt_lo_u32_b32 v0, s6, 0
	v_mbcnt_hi_u32_b32 v0, s7, v0
	v_cmp_eq_u32_e32 vcc, 0, v0
	s_and_saveexec_b64 s[10:11], vcc
	s_cbranch_execz .LBB0_581
	s_bcnt1_i32_b64 s3, s[6:7]
	v_readlane_b32 s6, v252, 55
	v_mov_b32_e32 v0, s3
	v_readlane_b32 s7, v252, 56
	s_nop 4

; __device__ __forceinline__ unsigned xb_ld(unsigned* p)              { return __hip_atomic_load(p, __ATOMIC_RELAXED, __HIP_MEMORY_SCOPE_AGENT); }
; __device__ __forceinline__ unsigned xb_add(unsigned* p, unsigned v) { return __hip_atomic_fetch_add(p, v, __ATOMIC_RELAXED, __HIP_MEMORY_SCOPE_AGENT); }
; #define XB_SPIN(cond, bar) do { unsigned _sp = 0; while (cond) { __builtin_amdgcn_s_sleep(1); \
;     if ((++_sp & 255u) == 0u) { if (xb_ld(&(bar)[XB_TMO])) break; if (_sp > XB_SPIN_CAP) { atomicAdd(&(bar)[XB_TMO], 1u); break; } } } } while (0)
; __device__ __forceinline__ void xcd_barrier(const XcdBarrier& b, bool leader_thread) {
;     ...
;             if (og + 1u == (tg + 1u) * nx) xb_add(&bar[XB_TOPGEN], 1u);
;             else XB_SPIN(xb_ld(&bar[XB_TOPGEN]) == tg, bar);
;             __builtin_amdgcn_fence(__ATOMIC_ACQUIRE, "agent");
;             xb_add(&bar[XB_XGEN(b.x)], 1u);
;             asm volatile("s_waitcnt vmcnt(0)" ::: "memory");
.LBB0_794:
	s_or_b64 exec, exec, s[6:7]
	s_mov_b64 s[6:7], exec
	v_mbcnt_lo_u32_b32 v0, s6, 0
	v_mbcnt_hi_u32_b32 v0, s7, v0
	v_cmp_eq_u32_e32 vcc, 0, v0
	s_and_saveexec_b64 s[8:9], vcc
	s_cbranch_execz .LBB0_796
	s_bcnt1_i32_b64 s3, s[6:7]
	v_readlane_b32 s6, v252, 55
	v_mov_b32_e32 v0, s3
	v_readlane_b32 s7, v252, 56
	s_nop 4

; __device__ __forceinline__ unsigned xb_add(unsigned* p, unsigned v) { return __hip_atomic_fetch_add(p, v, __ATOMIC_RELAXED, __HIP_MEMORY_SCOPE_AGENT); }
; __device__ __forceinline__ void xcd_barrier(const XcdBarrier& b, bool leader_thread) {
;     ...
;             __builtin_amdgcn_fence(__ATOMIC_ACQUIRE, "agent");
;             xb_add(&bar[XB_XGEN(b.x)], 1u);
;             asm volatile("s_waitcnt vmcnt(0)" ::: "memory");
.LBB0_1315:
	s_or_b64 exec, exec, s[4:5]
	s_mov_b64 s[4:5], exec
	v_mbcnt_lo_u32_b32 v0, s4, 0
	v_mbcnt_hi_u32_b32 v0, s5, v0
	v_cmp_eq_u32_e32 vcc, 0, v0
	buffer_inv sc1
	s_and_saveexec_b64 s[6:7], vcc
	s_cbranch_execnz .LBB0_1316
	s_getpc_b64 s[98:99]

; __device__ __forceinline__ unsigned xb_add(unsigned* p, unsigned v) { return __hip_atomic_fetch_add(p, v, __ATOMIC_RELAXED, __HIP_MEMORY_SCOPE_AGENT); }
; __device__ __forceinline__ void xcd_barrier(const XcdBarrier& b, bool leader_thread) {
;     ...
;             xb_add(&bar[XB_XGEN(b.x)], 1u);
.LBB0_1316:
	s_bcnt1_i32_b64 s2, s[4:5]
	v_mov_b32_e32 v0, s2
	v_readlane_b32 s2, v252, 55
	v_readlane_b32 s3, v252, 56
	s_nop 4
	s_getpc_b64 s[98:99]
